# diff-attn unit prologue: LUT/Q/K0/V0/K1 loads issued together, LDS stores behind counted waits
# speedup vs baseline: 1.0034x; 1.0034x over previous
.LBB0_295:
	s_movk_i32 s2, 0x21f
	v_cmp_lt_i32_e32 vcc, s2, v159
	v_lshlrev_b32_e32 v160, 2, v159
	s_and_saveexec_b64 s[2:3], vcc
	s_xor_b64 s[2:3], exec, s[2:3]
	v_lshlrev_b32_e32 v160, 2, v159
	s_or_saveexec_b64 s[2:3], s[2:3]
	s_and_b32 s21, s14, 7
	s_xor_b64 exec, exec, s[2:3]
	s_cbranch_execz .LBB0_301
	s_mul_i32 s4, s21, 0x2200
	v_readlane_b32 s5, v253, 5
	s_add_u32 s4, s5, s4
	v_readlane_b32 s5, v253, 6
	s_addc_u32 s5, s5, 0
	s_add_i32 s12, 0, 0x18000
	v_add_u32_e32 v2, 0xfffffe00, v159
	v_lshl_add_u32 v228, v159, 4, s12
	s_mov_b64 s[12:13], 0
	v_mov_b32_e32 v0, v160
.LBB0_299:
	v_ashrrev_i32_e32 v1, 31, v0
	v_lshl_add_u64 v[4:5], v[0:1], 2, s[4:5]
	global_load_dwordx4 v[220:223], v[4:5], off
	v_cmp_gt_i32_e32 vcc, 32, v159
	s_and_saveexec_b64 s[12:13], vcc
	s_cbranch_execz .Lda_lut2_skip
	v_add_u32_e32 v0, 0x800, v0
	v_ashrrev_i32_e32 v1, 31, v0
	v_lshl_add_u64 v[4:5], v[0:1], 2, s[4:5]
	global_load_dwordx4 v[224:227], v[4:5], off
.Lda_lut2_skip:
	s_mov_b64 exec, s[12:13]
.LBB0_301:
	s_or_b64 exec, exec, s[2:3]
	s_ashr_i32 s12, s14, 3
	s_ashr_i32 s13, s12, 31
	s_lshl_b64 s[2:3], s[12:13], 13
	s_lshl_b32 s13, s22, 7
	v_and_b32_e32 v4, 31, v159
	s_ashr_i32 s4, s13, 31
	v_and_b32_e32 v0, 63, v159
	s_add_u32 s5, s2, s13
	v_or_b32_e32 v158, s17, v4
	v_lshlrev_b32_e32 v0, 4, v0
	v_or_b32_e32 v146, s5, v158
	v_mov_b64_e32 v[6:7], s[48:49]
	v_add_u32_e32 v162, s16, v0
	s_addc_u32 s14, s3, s4
	v_mad_u64_u32 v[0:1], s[4:5], v146, s53, v[6:7]
	v_mad_i32_i24 v1, s14, v216, v1
	s_lshl_b32 s90, s21, 8
	v_bfe_u32 v5, v159, 5, 1
	v_lshl_add_u64 v[0:1], v[0:1], 0, s[90:91]
	v_lshl_add_u64 v[0:1], s[6:7], 1, v[0:1]
	v_lshlrev_b32_e32 v168, 4, v5
	v_lshl_add_u64 v[8:9], v[0:1], 0, v[168:169]
	global_load_dwordx4 v[112:115], v[8:9], off
	global_load_dwordx4 v[116:119], v[8:9], off offset:32
	global_load_dwordx4 v[120:123], v[8:9], off offset:64
	global_load_dwordx4 v[124:127], v[8:9], off offset:96
	v_ashrrev_i32_e32 v128, 3, v159
	v_ashrrev_i32_e32 v129, 31, v128
	v_ashrrev_i32_e32 v130, 4, v159
	v_mov_b32_e32 v23, v169
	v_ashrrev_i32_e32 v131, 31, v130
	s_or_b32 s23, s13, s17
	v_lshlrev_b32_e32 v157, 2, v5
	v_or_b32_e32 v5, s23, v4
	s_cmpk_gt_i32 s23, 0x627
	v_mov_b32_e32 v147, s14
	v_lshlrev_b32_e32 v8, 4, v159
	v_and_b32_e32 v22, 0x70, v8
	v_lshl_add_u64 v[0:1], s[2:3], 0, v[128:129]
	v_mad_u64_u32 v[2:3], s[4:5], v0, s53, v[6:7]
	v_mad_i32_i24 v3, v1, s53, v3
	v_lshl_add_u64 v[0:1], v[2:3], 0, s[90:91]
	v_lshl_add_u64 v[2:3], v[0:1], 0, v[22:23]
	v_lshl_add_u64 v[0:1], s[2:3], 0, v[130:131]
	v_mad_u64_u32 v[6:7], s[2:3], v0, s53, v[6:7]
	v_mad_i32_i24 v7, v1, s53, v7
	s_movk_i32 s2, 0x90
	v_lshl_add_u64 v[0:1], v[6:7], 0, s[90:91]
	v_and_b32_e32 v6, 0xf0, v8
	v_mov_b32_e32 v7, v169
	v_mul_lo_u32 v23, v128, s2
	s_movk_i32 s2, 0x140
	v_mad_u64_u32 v[132:133], s[2:3], v130, s2, v[6:7]
	v_lshl_add_u64 v[0:1], v[0:1], 0, v[6:7]
	s_movk_i32 s2, 0x1000
	v_add_co_u32_e32 v14, vcc, s2, v0
	s_mov_b32 s2, 0x31000
	s_nop 0
	v_addc_co_u32_e32 v15, vcc, 0, v1, vcc
	global_load_dwordx4 v[6:9], v[2:3], off offset:2048
	global_load_dwordx4 v[10:13], v[2:3], off offset:2176
	v_add_co_u32_e32 v18, vcc, s2, v0
	global_load_dwordx4 v[14:17], v[14:15], off
	s_nop 0
	v_addc_co_u32_e32 v19, vcc, 0, v1, vcc
	global_load_dwordx4 v[18:21], v[18:19], off
	v_add_co_u32_e32 v56, vcc, 0x60000, v2
	s_nop 1
	v_addc_co_u32_e32 v57, vcc, 0, v3, vcc
	global_load_dwordx4 v[48:51], v[56:57], off offset:2048
	global_load_dwordx4 v[52:55], v[56:57], off offset:2176
	v_add3_u32 v163, v23, v22, 0
	s_mov_b32 s2, 0x60000
	v_add_u32_e32 v164, 0, v132
	s_cselect_b64 s[4:5], -1, 0
	s_cmpk_lt_i32 s23, 0x628
	v_sub_u32_e32 v129, v5, v157
	s_waitcnt vmcnt(10)
	ds_write_b128 v228, v[220:223]
	s_mov_b64 s[62:63], exec
	v_cmpx_gt_i32_e32 vcc, 32, v159
	s_nop 1
	ds_write_b128 v228, v[224:227] offset:8192
	s_mov_b64 exec, s[62:63]
	s_waitcnt vmcnt(6)
	ds_write_b128 v162, v[112:115]
	ds_write_b128 v162, v[116:119] offset:1024
	ds_write_b128 v162, v[120:123] offset:2048
	ds_write_b128 v162, v[124:127] offset:3072
	s_waitcnt vmcnt(5)
	ds_write_b128 v163, v[6:9]
	s_waitcnt vmcnt(4)
	ds_write_b128 v163, v[10:13] offset:9216
	s_waitcnt vmcnt(3)
	ds_write_b128 v164, v[14:17] offset:36864
	s_waitcnt vmcnt(2)
	ds_write_b128 v164, v[18:21] offset:47104
	v_readlane_b32 s2, v254, 57
	s_waitcnt vmcnt(1)
	ds_write_b128 v163, v[48:51] offset:18432
	s_waitcnt vmcnt(0)
	ds_write_b128 v163, v[52:55] offset:27648
	s_nop 0
	s_nop 0
	s_nop 0
	s_nop 0
	s_nop 0
	s_nop 0
	s_nop 0
	s_nop 0
	s_nop 0
	s_nop 0
	s_nop 0
	s_nop 0
	s_nop 0
	s_nop 0
	s_nop 0
	s_nop 0
	s_nop 0
	s_nop 0
	s_nop 0
	s_nop 0
	s_nop 0
	s_nop 0
	s_nop 0
	s_nop 0
	s_nop 0
	s_nop 0
	s_nop 0
	s_nop 0
	s_nop 0
	s_nop 0
	s_nop 0
	s_nop 0
	s_nop 0
	s_nop 0
	s_nop 0
	s_nop 0
	s_nop 0
	s_nop 0
	s_nop 0
	s_nop 0
	s_nop 0
	s_nop 0
	s_nop 0
	s_nop 0
	s_nop 0
	s_nop 0
	s_nop 0
	s_nop 0
	s_nop 0
	s_nop 0
	s_nop 0
	s_nop 0
	s_nop 0
	s_nop 0
	s_nop 0
	s_nop 0
	s_nop 0
	s_nop 0
	v_mov_b32_e32 v6, s2
	s_waitcnt lgkmcnt(0)
	s_barrier
	ds_read_b32 v165, v6
	s_mov_b64 s[2:3], -1
	s_cbranch_scc0 .LBB0_303
	s_add_i32 s2, 0, 0x18000
	v_lshl_add_u32 v5, v129, 2, s2
	ds_read2_b32 v[6:7], v5 offset0:127 offset1:128
	ds_read2_b32 v[8:9], v5 offset0:125 offset1:126
	ds_read2_b32 v[10:11], v5 offset0:119 offset1:120
	ds_read2_b32 v[12:13], v5 offset0:117 offset1:118
	ds_read2_b32 v[14:15], v5 offset0:95 offset1:96
	ds_read2_b32 v[32:33], v5 offset0:93 offset1:94
	ds_read2_b32 v[34:35], v5 offset0:87 offset1:88
	ds_read2_b32 v[36:37], v5 offset0:85 offset1:86
	ds_read2_b32 v[16:17], v5 offset0:111 offset1:112
	ds_read2_b32 v[18:19], v5 offset0:109 offset1:110
	ds_read2_b32 v[20:21], v5 offset0:103 offset1:104
	ds_read2_b32 v[22:23], v5 offset0:101 offset1:102
	ds_read2_b32 v[38:39], v5 offset0:79 offset1:80
	ds_read2_b32 v[40:41], v5 offset0:77 offset1:78
	ds_read2_b32 v[42:43], v5 offset0:71 offset1:72
	ds_read2_b32 v[56:57], v5 offset0:69 offset1:70
	s_mov_b64 s[2:3], 0
	s_waitcnt lgkmcnt(4)
	v_mov_b32_e32 v31, v22
	v_mov_b32_e32 v30, v23
	v_mov_b32_e32 v29, v20
	v_mov_b32_e32 v28, v21
	v_mov_b32_e32 v27, v18
	v_mov_b32_e32 v26, v19
	v_mov_b32_e32 v25, v16
	v_mov_b32_e32 v24, v17
	v_mov_b32_e32 v23, v12
	v_mov_b32_e32 v22, v13
	v_mov_b32_e32 v21, v10
	v_mov_b32_e32 v20, v11
	v_mov_b32_e32 v19, v8
	v_mov_b32_e32 v18, v9
	v_mov_b32_e32 v17, v6
	v_mov_b32_e32 v16, v7
	s_waitcnt lgkmcnt(0)
	v_mov_b32_e32 v46, v57
	v_mov_b32_e32 v45, v42
	v_mov_b32_e32 v44, v43
	v_mov_b32_e32 v43, v40
	v_mov_b32_e32 v42, v41
	v_mov_b32_e32 v41, v38
	v_mov_b32_e32 v40, v39
	v_mov_b32_e32 v39, v36
	v_mov_b32_e32 v38, v37
	v_mov_b32_e32 v37, v34
	v_mov_b32_e32 v36, v35
	v_mov_b32_e32 v35, v32
	v_mov_b32_e32 v34, v33
	v_mov_b32_e32 v33, v14
	v_mov_b32_e32 v32, v15
	v_mov_b32_e32 v47, v56
